# SwiGLU epilogue: the -log2e multiply and the 1+e add done as packed f32 ops on register pairs (bit-identical)
# baseline (speedup 1.0000x reference)
.LBB0_660:
	s_add_u32 s48, s46, 0xfffc0080
	s_addc_u32 s49, s47, -1
	s_add_i32 s87, 0, 0x10000
	v_add_u32_e32 v156, s87, v145
	ds_read_b128 v[140:143], v156
	ds_read_b128 v[148:151], v156 offset:1024
	ds_read_b128 v[152:155], v156 offset:2048
	ds_read_b128 v[156:159], v156 offset:3072
	s_cmp_eq_u32 s86, 12
	s_cselect_b32 s63, s15, s49
	s_cselect_b32 s62, s82, s48
	s_cselect_b32 s49, s9, s85
	s_cselect_b32 s48, s83, s84
	v_lshl_add_u64 v[192:193], s[46:47], 0, v[138:139]
	s_add_i32 m0, s45, 0xc000
	ds_read_b128 v[160:163], v147
	ds_read_b128 v[164:167], v147 offset:1024
	ds_read_b128 v[168:171], v147 offset:2048
	ds_read_b128 v[172:175], v147 offset:3072
	ds_read_b128 v[176:179], v147 offset:4096
	ds_read_b128 v[180:183], v147 offset:5120
	ds_read_b128 v[184:187], v147 offset:6144
	ds_read_b128 v[188:191], v147 offset:7168
	global_load_lds_dwordx4 v[192:193], off
	v_lshl_add_u64 v[192:193], s[46:47], 0, v[136:137]
	s_add_i32 m0, s45, 0xe000
	s_nop 0
	global_load_lds_dwordx4 v[192:193], off
	s_waitcnt lgkmcnt(8)
	s_barrier
	s_waitcnt lgkmcnt(0)
	s_waitcnt lgkmcnt(0)
	v_mfma_f32_16x16x32_bf16 v[126:129], v[140:143], v[160:163], v[126:129]
	v_mfma_f32_16x16x32_bf16 v[122:125], v[152:155], v[160:163], v[122:125]
	v_mfma_f32_16x16x32_bf16 v[110:113], v[140:143], v[168:171], v[110:113]
	v_mfma_f32_16x16x32_bf16 v[106:109], v[152:155], v[168:171], v[106:109]
	v_mfma_f32_16x16x32_bf16 v[94:97], v[140:143], v[176:179], v[94:97]
	v_mfma_f32_16x16x32_bf16 v[90:93], v[152:155], v[176:179], v[90:93]
	v_mfma_f32_16x16x32_bf16 v[78:81], v[140:143], v[184:187], v[78:81]
	v_mfma_f32_16x16x32_bf16 v[74:77], v[152:155], v[184:187], v[74:77]
	v_mfma_f32_16x16x32_bf16 v[126:129], v[148:151], v[164:167], v[126:129]
	v_mfma_f32_16x16x32_bf16 v[122:125], v[156:159], v[164:167], v[122:125]
	v_mfma_f32_16x16x32_bf16 v[110:113], v[148:151], v[172:175], v[110:113]
	v_mfma_f32_16x16x32_bf16 v[106:109], v[156:159], v[172:175], v[106:109]
	v_mfma_f32_16x16x32_bf16 v[94:97], v[148:151], v[180:183], v[94:97]
	v_mfma_f32_16x16x32_bf16 v[90:93], v[156:159], v[180:183], v[90:93]
	v_mfma_f32_16x16x32_bf16 v[78:81], v[148:151], v[188:191], v[78:81]
	v_mfma_f32_16x16x32_bf16 v[74:77], v[156:159], v[188:191], v[74:77]
	s_barrier
	s_add_i32 s90, 0, 0x14000
	v_add_u32_e32 v192, s90, v145
	s_add_i32 s87, s87, s66
	ds_read_b128 v[196:199], v192
	ds_read_b128 v[204:207], v192 offset:1024
	ds_read_b128 v[208:211], v192 offset:2048
	ds_read_b128 v[212:215], v192 offset:3072
	v_lshl_add_u64 v[192:193], s[48:49], 0, v[0:1]
	s_mov_b32 m0, s87
	v_lshl_add_u64 v[200:201], s[48:49], 0, v[130:131]
	global_load_lds_dwordx4 v[192:193], off
	s_add_i32 m0, s87, 0x2000
	s_nop 0
	global_load_lds_dwordx4 v[200:201], off
	s_barrier
	s_waitcnt lgkmcnt(0)
	s_waitcnt lgkmcnt(0)
	v_mfma_f32_16x16x32_bf16 v[118:121], v[196:199], v[160:163], v[118:121]
	v_mfma_f32_16x16x32_bf16 v[114:117], v[208:211], v[160:163], v[114:117]
	v_mfma_f32_16x16x32_bf16 v[102:105], v[196:199], v[168:171], v[102:105]
	v_mfma_f32_16x16x32_bf16 v[98:101], v[208:211], v[168:171], v[98:101]
	v_mfma_f32_16x16x32_bf16 v[86:89], v[196:199], v[176:179], v[86:89]
	v_mfma_f32_16x16x32_bf16 v[82:85], v[208:211], v[176:179], v[82:85]
	v_mfma_f32_16x16x32_bf16 v[70:73], v[196:199], v[184:187], v[70:73]
	v_mfma_f32_16x16x32_bf16 v[66:69], v[208:211], v[184:187], v[66:69]
	v_mfma_f32_16x16x32_bf16 v[118:121], v[204:207], v[164:167], v[118:121]
	v_mfma_f32_16x16x32_bf16 v[114:117], v[212:215], v[164:167], v[114:117]
	v_mfma_f32_16x16x32_bf16 v[102:105], v[204:207], v[172:175], v[102:105]
	v_mfma_f32_16x16x32_bf16 v[98:101], v[212:215], v[172:175], v[98:101]
	v_mfma_f32_16x16x32_bf16 v[86:89], v[204:207], v[180:183], v[86:89]
	v_mfma_f32_16x16x32_bf16 v[82:85], v[212:215], v[180:183], v[82:85]
	v_mfma_f32_16x16x32_bf16 v[70:73], v[204:207], v[188:191], v[70:73]
	v_mfma_f32_16x16x32_bf16 v[66:69], v[212:215], v[188:191], v[66:69]
	s_mov_b32 m0, s45
	v_lshl_add_u64 v[202:203], s[62:63], 0, v[134:135]
	s_barrier
	ds_read_b128 v[160:163], v147 offset:16384
	ds_read_b128 v[164:167], v147 offset:17408
	ds_read_b128 v[168:171], v147 offset:18432
	ds_read_b128 v[172:175], v147 offset:19456
	ds_read_b128 v[176:179], v147 offset:20480
	ds_read_b128 v[180:183], v147 offset:21504
	ds_read_b128 v[184:187], v147 offset:22528
	ds_read_b128 v[188:191], v147 offset:23552
	global_load_lds_dwordx4 v[202:203], off
	v_lshl_add_u64 v[216:217], s[62:63], 0, v[132:133]
	s_mov_b32 m0, s68
	s_nop 0
	global_load_lds_dwordx4 v[216:217], off
	s_barrier
	s_waitcnt lgkmcnt(0)
	s_waitcnt lgkmcnt(0)
	v_mfma_f32_16x16x32_bf16 v[62:65], v[140:143], v[160:163], v[62:65]
	v_mfma_f32_16x16x32_bf16 v[58:61], v[152:155], v[160:163], v[58:61]
	v_mfma_f32_16x16x32_bf16 v[46:49], v[140:143], v[168:171], v[46:49]
	v_mfma_f32_16x16x32_bf16 v[42:45], v[152:155], v[168:171], v[42:45]
	v_mfma_f32_16x16x32_bf16 v[30:33], v[140:143], v[176:179], v[30:33]
	v_mfma_f32_16x16x32_bf16 v[26:29], v[152:155], v[176:179], v[26:29]
	v_mfma_f32_16x16x32_bf16 v[14:17], v[140:143], v[184:187], v[14:17]
	v_mfma_f32_16x16x32_bf16 v[10:13], v[152:155], v[184:187], v[10:13]
	v_mfma_f32_16x16x32_bf16 v[62:65], v[148:151], v[164:167], v[62:65]
	v_mfma_f32_16x16x32_bf16 v[58:61], v[156:159], v[164:167], v[58:61]
	v_mfma_f32_16x16x32_bf16 v[46:49], v[148:151], v[172:175], v[46:49]
	v_mfma_f32_16x16x32_bf16 v[42:45], v[156:159], v[172:175], v[42:45]
	v_mfma_f32_16x16x32_bf16 v[30:33], v[148:151], v[180:183], v[30:33]
	v_mfma_f32_16x16x32_bf16 v[26:29], v[156:159], v[180:183], v[26:29]
	v_mfma_f32_16x16x32_bf16 v[14:17], v[148:151], v[188:191], v[14:17]
	v_mfma_f32_16x16x32_bf16 v[10:13], v[156:159], v[188:191], v[10:13]
	s_barrier
	s_add_u32 s88, s48, 0x40000
	s_addc_u32 s89, s49, 0
	s_add_i32 s87, s90, s66
	v_lshl_add_u64 v[140:141], s[88:89], 0, v[0:1]
	s_mov_b32 m0, s87
	s_nop 0
	global_load_lds_dwordx4 v[140:141], off
	v_lshl_add_u64 v[140:141], s[88:89], 0, v[130:131]
	s_add_i32 m0, s87, 0x2000
	s_nop 0
	global_load_lds_dwordx4 v[140:141], off
	s_waitcnt vmcnt(6)
	s_barrier
	v_mfma_f32_16x16x32_bf16 v[54:57], v[196:199], v[160:163], v[54:57]
	v_mfma_f32_16x16x32_bf16 v[50:53], v[208:211], v[160:163], v[50:53]
	v_mfma_f32_16x16x32_bf16 v[38:41], v[196:199], v[168:171], v[38:41]
	v_mfma_f32_16x16x32_bf16 v[34:37], v[208:211], v[168:171], v[34:37]
	v_mfma_f32_16x16x32_bf16 v[22:25], v[196:199], v[176:179], v[22:25]
	v_mfma_f32_16x16x32_bf16 v[18:21], v[208:211], v[176:179], v[18:21]
	v_mfma_f32_16x16x32_bf16 v[6:9], v[196:199], v[184:187], v[6:9]
	v_mfma_f32_16x16x32_bf16 v[2:5], v[208:211], v[184:187], v[2:5]
	v_mfma_f32_16x16x32_bf16 v[54:57], v[204:207], v[164:167], v[54:57]
	v_mfma_f32_16x16x32_bf16 v[50:53], v[212:215], v[164:167], v[50:53]
	v_mfma_f32_16x16x32_bf16 v[38:41], v[204:207], v[172:175], v[38:41]
	v_mfma_f32_16x16x32_bf16 v[34:37], v[212:215], v[172:175], v[34:37]
	v_mfma_f32_16x16x32_bf16 v[22:25], v[204:207], v[180:183], v[22:25]
	v_mfma_f32_16x16x32_bf16 v[18:21], v[212:215], v[180:183], v[18:21]
	v_mfma_f32_16x16x32_bf16 v[6:9], v[204:207], v[188:191], v[6:9]
	v_mfma_f32_16x16x32_bf16 v[2:5], v[212:215], v[188:191], v[2:5]
	s_add_i32 s87, 0, 0x18000
	v_add_u32_e32 v156, s87, v145
	s_barrier
	ds_read_b128 v[140:143], v156
	ds_read_b128 v[148:151], v156 offset:1024
	ds_read_b128 v[152:155], v156 offset:2048
	ds_read_b128 v[156:159], v156 offset:3072
	s_add_u32 s62, s62, 0x40000
	s_addc_u32 s63, s63, 0
	s_mov_b32 m0, s69
	v_lshl_add_u64 v[196:197], s[62:63], 0, v[134:135]
	ds_read_b128 v[160:163], v147 offset:32768
	ds_read_b128 v[164:167], v147 offset:33792
	ds_read_b128 v[168:171], v147 offset:34816
	ds_read_b128 v[172:175], v147 offset:35840
	ds_read_b128 v[176:179], v147 offset:36864
	ds_read_b128 v[180:183], v147 offset:37888
	ds_read_b128 v[184:187], v147 offset:38912
	ds_read_b128 v[188:191], v147 offset:39936
	global_load_lds_dwordx4 v[196:197], off
	v_lshl_add_u64 v[196:197], s[62:63], 0, v[132:133]
	s_mov_b32 m0, s70
	s_nop 0
	global_load_lds_dwordx4 v[196:197], off
	s_waitcnt lgkmcnt(8)
	s_barrier
	s_waitcnt lgkmcnt(0)
	s_waitcnt lgkmcnt(0)
	v_mfma_f32_16x16x32_bf16 v[126:129], v[140:143], v[160:163], v[126:129]
	v_mfma_f32_16x16x32_bf16 v[122:125], v[152:155], v[160:163], v[122:125]
	v_mfma_f32_16x16x32_bf16 v[110:113], v[140:143], v[168:171], v[110:113]
	v_mfma_f32_16x16x32_bf16 v[106:109], v[152:155], v[168:171], v[106:109]
	v_mfma_f32_16x16x32_bf16 v[94:97], v[140:143], v[176:179], v[94:97]
	v_mfma_f32_16x16x32_bf16 v[90:93], v[152:155], v[176:179], v[90:93]
	v_mfma_f32_16x16x32_bf16 v[78:81], v[140:143], v[184:187], v[78:81]
	v_mfma_f32_16x16x32_bf16 v[74:77], v[152:155], v[184:187], v[74:77]
	v_mfma_f32_16x16x32_bf16 v[126:129], v[148:151], v[164:167], v[126:129]
	v_mfma_f32_16x16x32_bf16 v[122:125], v[156:159], v[164:167], v[122:125]
	v_mfma_f32_16x16x32_bf16 v[110:113], v[148:151], v[172:175], v[110:113]
	v_mfma_f32_16x16x32_bf16 v[106:109], v[156:159], v[172:175], v[106:109]
	v_mfma_f32_16x16x32_bf16 v[94:97], v[148:151], v[180:183], v[94:97]
	v_mfma_f32_16x16x32_bf16 v[90:93], v[156:159], v[180:183], v[90:93]
	v_mfma_f32_16x16x32_bf16 v[78:81], v[148:151], v[188:191], v[78:81]
	v_mfma_f32_16x16x32_bf16 v[74:77], v[156:159], v[188:191], v[74:77]
	s_barrier
	s_add_i32 s62, 0, 0x1c000
	s_add_i32 s63, s87, s66
	v_add_u32_e32 v194, s62, v145
	v_lshl_add_u64 v[192:193], v[192:193], 0, s[12:13]
	s_mov_b32 m0, s63
	ds_read_b128 v[196:199], v194
	ds_read_b128 v[204:207], v194 offset:1024
	ds_read_b128 v[208:211], v194 offset:2048
	ds_read_b128 v[212:215], v194 offset:3072
	global_load_lds_dwordx4 v[192:193], off
	v_lshl_add_u64 v[192:193], v[200:201], 0, s[12:13]
	s_add_i32 m0, s63, 0x2000
	s_nop 0
	global_load_lds_dwordx4 v[192:193], off
	s_barrier
	s_waitcnt lgkmcnt(0)
	s_waitcnt lgkmcnt(0)
	v_mfma_f32_16x16x32_bf16 v[118:121], v[196:199], v[160:163], v[118:121]
	v_mfma_f32_16x16x32_bf16 v[114:117], v[208:211], v[160:163], v[114:117]
	v_mfma_f32_16x16x32_bf16 v[102:105], v[196:199], v[168:171], v[102:105]
	v_mfma_f32_16x16x32_bf16 v[98:101], v[208:211], v[168:171], v[98:101]
	v_mfma_f32_16x16x32_bf16 v[86:89], v[196:199], v[176:179], v[86:89]
	v_mfma_f32_16x16x32_bf16 v[82:85], v[208:211], v[176:179], v[82:85]
	v_mfma_f32_16x16x32_bf16 v[70:73], v[196:199], v[184:187], v[70:73]
	v_mfma_f32_16x16x32_bf16 v[66:69], v[208:211], v[184:187], v[66:69]
	v_mfma_f32_16x16x32_bf16 v[118:121], v[204:207], v[164:167], v[118:121]
	v_mfma_f32_16x16x32_bf16 v[114:117], v[212:215], v[164:167], v[114:117]
	v_mfma_f32_16x16x32_bf16 v[102:105], v[204:207], v[172:175], v[102:105]
	v_mfma_f32_16x16x32_bf16 v[98:101], v[212:215], v[172:175], v[98:101]
	v_mfma_f32_16x16x32_bf16 v[86:89], v[204:207], v[180:183], v[86:89]
	v_mfma_f32_16x16x32_bf16 v[82:85], v[212:215], v[180:183], v[82:85]
	v_mfma_f32_16x16x32_bf16 v[70:73], v[204:207], v[188:191], v[70:73]
	v_mfma_f32_16x16x32_bf16 v[66:69], v[212:215], v[188:191], v[66:69]
	s_mov_b32 m0, s71
	v_lshl_add_u64 v[192:193], v[202:203], 0, s[12:13]
	s_barrier
	ds_read_b128 v[160:163], v147 offset:49152
	ds_read_b128 v[164:167], v147 offset:50176
	ds_read_b128 v[168:171], v147 offset:51200
	ds_read_b128 v[172:175], v147 offset:52224
	ds_read_b128 v[176:179], v147 offset:53248
	ds_read_b128 v[180:183], v147 offset:54272
	ds_read_b128 v[184:187], v147 offset:55296
	ds_read_b128 v[188:191], v147 offset:56320
	global_load_lds_dwordx4 v[192:193], off
	v_lshl_add_u64 v[192:193], v[216:217], 0, s[12:13]
	s_mov_b32 m0, s78
	s_nop 0
	global_load_lds_dwordx4 v[192:193], off
	s_barrier
	s_waitcnt lgkmcnt(0)
	s_waitcnt lgkmcnt(0)
	v_mfma_f32_16x16x32_bf16 v[62:65], v[140:143], v[160:163], v[62:65]
	v_mfma_f32_16x16x32_bf16 v[58:61], v[152:155], v[160:163], v[58:61]
	v_mfma_f32_16x16x32_bf16 v[46:49], v[140:143], v[168:171], v[46:49]
	v_mfma_f32_16x16x32_bf16 v[42:45], v[152:155], v[168:171], v[42:45]
	v_mfma_f32_16x16x32_bf16 v[30:33], v[140:143], v[176:179], v[30:33]
	v_mfma_f32_16x16x32_bf16 v[26:29], v[152:155], v[176:179], v[26:29]
	v_mfma_f32_16x16x32_bf16 v[14:17], v[140:143], v[184:187], v[14:17]
	v_mfma_f32_16x16x32_bf16 v[10:13], v[152:155], v[184:187], v[10:13]
	v_mfma_f32_16x16x32_bf16 v[62:65], v[148:151], v[164:167], v[62:65]
	v_mfma_f32_16x16x32_bf16 v[58:61], v[156:159], v[164:167], v[58:61]
	v_mfma_f32_16x16x32_bf16 v[46:49], v[148:151], v[172:175], v[46:49]
	v_mfma_f32_16x16x32_bf16 v[42:45], v[156:159], v[172:175], v[42:45]
	v_mfma_f32_16x16x32_bf16 v[30:33], v[148:151], v[180:183], v[30:33]
	v_mfma_f32_16x16x32_bf16 v[26:29], v[156:159], v[180:183], v[26:29]
	v_mfma_f32_16x16x32_bf16 v[14:17], v[148:151], v[188:191], v[14:17]
	v_mfma_f32_16x16x32_bf16 v[10:13], v[156:159], v[188:191], v[10:13]
	s_barrier
	s_add_u32 s48, s48, 0x40080
	s_addc_u32 s49, s49, 0
	s_add_i32 s62, s62, s66
	v_lshl_add_u64 v[140:141], s[48:49], 0, v[0:1]
	s_mov_b32 m0, s62
	s_nop 0
	global_load_lds_dwordx4 v[140:141], off
	v_lshl_add_u64 v[140:141], s[48:49], 0, v[130:131]
	s_add_i32 m0, s62, 0x2000
	s_nop 0
	global_load_lds_dwordx4 v[140:141], off
	s_waitcnt vmcnt(6)
	s_barrier
	v_mfma_f32_16x16x32_bf16 v[54:57], v[196:199], v[160:163], v[54:57]
	v_mfma_f32_16x16x32_bf16 v[50:53], v[208:211], v[160:163], v[50:53]
	v_mfma_f32_16x16x32_bf16 v[38:41], v[196:199], v[168:171], v[38:41]
	v_mfma_f32_16x16x32_bf16 v[34:37], v[208:211], v[168:171], v[34:37]
	v_mfma_f32_16x16x32_bf16 v[22:25], v[196:199], v[176:179], v[22:25]
	v_mfma_f32_16x16x32_bf16 v[18:21], v[208:211], v[176:179], v[18:21]
	v_mfma_f32_16x16x32_bf16 v[6:9], v[196:199], v[184:187], v[6:9]
	v_mfma_f32_16x16x32_bf16 v[2:5], v[208:211], v[184:187], v[2:5]
	v_mfma_f32_16x16x32_bf16 v[54:57], v[204:207], v[164:167], v[54:57]
	v_mfma_f32_16x16x32_bf16 v[50:53], v[212:215], v[164:167], v[50:53]
	v_mfma_f32_16x16x32_bf16 v[38:41], v[204:207], v[172:175], v[38:41]
	v_mfma_f32_16x16x32_bf16 v[34:37], v[212:215], v[172:175], v[34:37]
	v_mfma_f32_16x16x32_bf16 v[22:25], v[204:207], v[180:183], v[22:25]
	v_mfma_f32_16x16x32_bf16 v[18:21], v[212:215], v[180:183], v[18:21]
	v_mfma_f32_16x16x32_bf16 v[6:9], v[204:207], v[188:191], v[6:9]
	v_mfma_f32_16x16x32_bf16 v[2:5], v[212:215], v[188:191], v[2:5]
	s_add_i32 s86, s86, 2
	s_add_u32 s84, s84, 0x100
	s_addc_u32 s85, s85, 0
	s_add_u32 s46, s46, 0x100
	s_addc_u32 s47, s47, 0
	s_cmp_gt_u32 s86, 13
	s_barrier
	s_cbranch_scc0 .LBB0_660
	s_mov_b32 s100, 0xbfb8aa3b
	s_nop 1
	v_pk_mul_f32 v[150:151], v[126:127], s[100:101] op_sel_hi:[1,0]
	v_exp_f32_e32 v150, v150
	v_exp_f32_e32 v151, v151
	s_nop 0
	v_pk_add_f32 v[150:151], v[150:151], 1.0 op_sel_hi:[1,0]
	v_rcp_f32_e32 v150, v150
	v_rcp_f32_e32 v151, v151
	s_nop 0
	v_lshl_or_b32 v142, s81, 7, v146
	v_lshl_add_u32 v148, s44, 8, v144
	v_ashrrev_i32_e32 v143, 31, v142
	s_movk_i32 s9, 0x1600
	v_lshlrev_b64 v[142:143], 1, v[142:143]
	s_and_b64 vcc, exec, s[40:41]
	s_nop 1
	v_pk_mul_f32 v[152:153], v[128:129], s[100:101] op_sel_hi:[1,0]
	v_exp_f32_e32 v152, v152
	v_exp_f32_e32 v153, v153
	s_nop 0
	v_pk_add_f32 v[152:153], v[152:153], 1.0 op_sel_hi:[1,0]
	v_rcp_f32_e32 v152, v152
	v_rcp_f32_e32 v153, v153
	s_nop 0
	s_mov_b32 s81, s8
	v_pk_mul_f32 v[126:127], v[126:127], v[150:151]
	s_mov_b32 s44, s14
	v_pk_mul_f32 v[118:119], v[126:127], v[118:119]
	s_mov_b64 s[48:49], s[16:17]
	v_cvt_pk_bf16_f32 v118, v118, v119
	s_nop 1
	v_pk_mul_f32 v[154:155], v[122:123], s[100:101] op_sel_hi:[1,0]
	v_exp_f32_e32 v154, v154
	v_exp_f32_e32 v155, v155
	s_nop 0
	v_pk_add_f32 v[154:155], v[154:155], 1.0 op_sel_hi:[1,0]
	v_rcp_f32_e32 v154, v154
	v_rcp_f32_e32 v155, v155
	s_nop 0
	v_pk_mul_f32 v[126:127], v[128:129], v[152:153]
	s_nop 0
	v_pk_mul_f32 v[120:121], v[126:127], v[120:121]
	v_cvt_pk_bf16_f32 v119, v120, v121
	s_nop 1
	v_pk_mul_f32 v[156:157], v[124:125], s[100:101] op_sel_hi:[1,0]
	v_exp_f32_e32 v156, v156
	v_exp_f32_e32 v157, v157
	s_nop 0
	v_pk_add_f32 v[156:157], v[156:157], 1.0 op_sel_hi:[1,0]
	v_rcp_f32_e32 v156, v156
	v_rcp_f32_e32 v157, v157
	s_nop 0
	v_pk_mul_f32 v[120:121], v[122:123], v[154:155]
	s_nop 0
	v_pk_mul_f32 v[114:115], v[120:121], v[114:115]
	v_cvt_pk_bf16_f32 v120, v114, v115
	v_or_b32_e32 v122, 16, v148
	v_mov_b64_e32 v[140:141], s[4:5]
	v_mad_i64_i32 v[158:159], s[46:47], v148, s9, v[140:141]
	v_pk_mul_f32 v[114:115], v[124:125], v[156:157]
	v_lshl_add_u64 v[158:159], v[158:159], 0, v[142:143]
	v_pk_mul_f32 v[114:115], v[114:115], v[116:117]
	s_nop 1
	v_pk_mul_f32 v[116:117], v[112:113], s[100:101] op_sel_hi:[1,0]
	v_exp_f32_e32 v116, v116
	v_exp_f32_e32 v117, v117
	s_nop 0
	v_pk_add_f32 v[116:117], v[116:117], 1.0 op_sel_hi:[1,0]
	v_rcp_f32_e32 v116, v116
	v_rcp_f32_e32 v117, v117
	s_nop 0
	v_cvt_pk_bf16_f32 v121, v114, v115
	s_nop 1
	v_pk_mul_f32 v[114:115], v[110:111], s[100:101] op_sel_hi:[1,0]
	v_exp_f32_e32 v114, v114
	v_exp_f32_e32 v115, v115
	s_nop 0
	v_pk_add_f32 v[114:115], v[114:115], 1.0 op_sel_hi:[1,0]
	v_rcp_f32_e32 v114, v114
	v_rcp_f32_e32 v115, v115
	s_nop 0
	global_store_dwordx4 v[158:159], v[118:121], off
	s_nop 1
	v_pk_mul_f32 v[118:119], v[106:107], s[100:101] op_sel_hi:[1,0]
	v_exp_f32_e32 v118, v118
	v_exp_f32_e32 v119, v119
	s_nop 0
	v_pk_add_f32 v[118:119], v[118:119], 1.0 op_sel_hi:[1,0]
	v_rcp_f32_e32 v118, v118
	v_rcp_f32_e32 v119, v119
	s_nop 0
	s_nop 1
	v_pk_mul_f32 v[120:121], v[108:109], s[100:101] op_sel_hi:[1,0]
	v_exp_f32_e32 v120, v120
	v_exp_f32_e32 v121, v121
	s_nop 0
	v_pk_add_f32 v[120:121], v[120:121], 1.0 op_sel_hi:[1,0]
	v_rcp_f32_e32 v120, v120
	v_rcp_f32_e32 v121, v121
	s_nop 0
	v_pk_mul_f32 v[110:111], v[110:111], v[114:115]
	v_pk_mul_f32 v[102:103], v[110:111], v[102:103]
	v_pk_mul_f32 v[110:111], v[112:113], v[116:117]
	v_cvt_pk_bf16_f32 v102, v102, v103
	v_pk_mul_f32 v[104:105], v[110:111], v[104:105]
	v_mad_i64_i32 v[122:123], s[46:47], v122, s9, v[140:141]
	v_cvt_pk_bf16_f32 v103, v104, v105
	v_pk_mul_f32 v[104:105], v[106:107], v[118:119]
	v_lshl_add_u64 v[122:123], v[122:123], 0, v[142:143]
	v_pk_mul_f32 v[98:99], v[104:105], v[98:99]
	v_or_b32_e32 v106, 32, v148
	v_cvt_pk_bf16_f32 v104, v98, v99
	v_pk_mul_f32 v[98:99], v[108:109], v[120:121]
	v_mad_i64_i32 v[106:107], s[46:47], v106, s9, v[140:141]
	v_pk_mul_f32 v[98:99], v[98:99], v[100:101]
	s_nop 1
	v_pk_mul_f32 v[100:101], v[96:97], s[100:101] op_sel_hi:[1,0]
	v_exp_f32_e32 v100, v100
	v_exp_f32_e32 v101, v101
	s_nop 0
	v_pk_add_f32 v[100:101], v[100:101], 1.0 op_sel_hi:[1,0]
	v_rcp_f32_e32 v100, v100
	v_rcp_f32_e32 v101, v101
	s_nop 0
	v_cvt_pk_bf16_f32 v105, v98, v99
	s_nop 1
	v_pk_mul_f32 v[98:99], v[94:95], s[100:101] op_sel_hi:[1,0]
	v_exp_f32_e32 v98, v98
	v_exp_f32_e32 v99, v99
	s_nop 0
	v_pk_add_f32 v[98:99], v[98:99], 1.0 op_sel_hi:[1,0]
	v_rcp_f32_e32 v98, v98
	v_rcp_f32_e32 v99, v99
	s_nop 0
	global_store_dwordx4 v[122:123], v[102:105], off
	s_nop 1
	v_pk_mul_f32 v[102:103], v[90:91], s[100:101] op_sel_hi:[1,0]
	v_exp_f32_e32 v102, v102
	v_exp_f32_e32 v103, v103
	s_nop 0
	v_pk_add_f32 v[102:103], v[102:103], 1.0 op_sel_hi:[1,0]
	v_rcp_f32_e32 v102, v102
	v_rcp_f32_e32 v103, v103
	s_nop 0
	s_nop 1
	v_pk_mul_f32 v[104:105], v[92:93], s[100:101] op_sel_hi:[1,0]
	v_exp_f32_e32 v104, v104
	v_exp_f32_e32 v105, v105
	s_nop 0
	v_pk_add_f32 v[104:105], v[104:105], 1.0 op_sel_hi:[1,0]
	v_rcp_f32_e32 v104, v104
	v_rcp_f32_e32 v105, v105
	s_nop 0
	v_pk_mul_f32 v[94:95], v[94:95], v[98:99]
	v_pk_mul_f32 v[86:87], v[94:95], v[86:87]
	v_pk_mul_f32 v[94:95], v[96:97], v[100:101]
	v_cvt_pk_bf16_f32 v86, v86, v87
	v_pk_mul_f32 v[88:89], v[94:95], v[88:89]
	v_lshl_add_u64 v[106:107], v[106:107], 0, v[142:143]
	v_cvt_pk_bf16_f32 v87, v88, v89
	v_pk_mul_f32 v[88:89], v[90:91], v[102:103]
	v_or_b32_e32 v90, 48, v148
	v_pk_mul_f32 v[82:83], v[88:89], v[82:83]
	v_mad_i64_i32 v[90:91], s[46:47], v90, s9, v[140:141]
	v_cvt_pk_bf16_f32 v88, v82, v83
	v_pk_mul_f32 v[82:83], v[92:93], v[104:105]
	v_lshl_add_u64 v[90:91], v[90:91], 0, v[142:143]
	v_pk_mul_f32 v[82:83], v[82:83], v[84:85]
	s_nop 1
	v_pk_mul_f32 v[84:85], v[80:81], s[100:101] op_sel_hi:[1,0]
	v_exp_f32_e32 v84, v84
	v_exp_f32_e32 v85, v85
	s_nop 0
	v_pk_add_f32 v[84:85], v[84:85], 1.0 op_sel_hi:[1,0]
	v_rcp_f32_e32 v84, v84
	v_rcp_f32_e32 v85, v85
	s_nop 0
	v_cvt_pk_bf16_f32 v89, v82, v83
	s_nop 1
	v_pk_mul_f32 v[82:83], v[78:79], s[100:101] op_sel_hi:[1,0]
	v_exp_f32_e32 v82, v82
	v_exp_f32_e32 v83, v83
	s_nop 0
	v_pk_add_f32 v[82:83], v[82:83], 1.0 op_sel_hi:[1,0]
	v_rcp_f32_e32 v82, v82
	v_rcp_f32_e32 v83, v83
	s_nop 0
	global_store_dwordx4 v[106:107], v[86:89], off
	s_nop 1
	v_pk_mul_f32 v[86:87], v[74:75], s[100:101] op_sel_hi:[1,0]
	v_exp_f32_e32 v86, v86
	v_exp_f32_e32 v87, v87
	s_nop 0
	v_pk_add_f32 v[86:87], v[86:87], 1.0 op_sel_hi:[1,0]
	v_rcp_f32_e32 v86, v86
	v_rcp_f32_e32 v87, v87
	s_nop 0
	s_nop 1
	v_pk_mul_f32 v[88:89], v[76:77], s[100:101] op_sel_hi:[1,0]
	v_exp_f32_e32 v88, v88
	v_exp_f32_e32 v89, v89
	s_nop 0
	v_pk_add_f32 v[88:89], v[88:89], 1.0 op_sel_hi:[1,0]
	v_rcp_f32_e32 v88, v88
	v_rcp_f32_e32 v89, v89
	s_nop 0
	v_pk_mul_f32 v[78:79], v[78:79], v[82:83]
	v_pk_mul_f32 v[70:71], v[78:79], v[70:71]
	v_pk_mul_f32 v[78:79], v[80:81], v[84:85]
	v_cvt_pk_bf16_f32 v70, v70, v71
	v_pk_mul_f32 v[72:73], v[78:79], v[72:73]
	s_nop 0
	v_cvt_pk_bf16_f32 v71, v72, v73
	v_pk_mul_f32 v[72:73], v[74:75], v[86:87]
	v_add_u32_e32 v74, 0x80, v148
	v_pk_mul_f32 v[66:67], v[72:73], v[66:67]
	v_mad_i64_i32 v[74:75], s[46:47], v74, s9, v[140:141]
	v_cvt_pk_bf16_f32 v72, v66, v67
	v_pk_mul_f32 v[66:67], v[76:77], v[88:89]
	v_lshl_add_u64 v[74:75], v[74:75], 0, v[142:143]
	v_pk_mul_f32 v[66:67], v[66:67], v[68:69]
	s_nop 1
	v_pk_mul_f32 v[68:69], v[64:65], s[100:101] op_sel_hi:[1,0]
	v_exp_f32_e32 v68, v68
	v_exp_f32_e32 v69, v69
	s_nop 0
	v_pk_add_f32 v[68:69], v[68:69], 1.0 op_sel_hi:[1,0]
	v_rcp_f32_e32 v68, v68
	v_rcp_f32_e32 v69, v69
	s_nop 0
	v_cvt_pk_bf16_f32 v73, v66, v67
	s_nop 1
	v_pk_mul_f32 v[66:67], v[62:63], s[100:101] op_sel_hi:[1,0]
	v_exp_f32_e32 v66, v66
	v_exp_f32_e32 v67, v67
	s_nop 0
	v_pk_add_f32 v[66:67], v[66:67], 1.0 op_sel_hi:[1,0]
	v_rcp_f32_e32 v66, v66
	v_rcp_f32_e32 v67, v67
	s_nop 0
	global_store_dwordx4 v[90:91], v[70:73], off
	s_nop 1
	v_pk_mul_f32 v[70:71], v[58:59], s[100:101] op_sel_hi:[1,0]
	v_exp_f32_e32 v70, v70
	v_exp_f32_e32 v71, v71
	s_nop 0
	v_pk_add_f32 v[70:71], v[70:71], 1.0 op_sel_hi:[1,0]
	v_rcp_f32_e32 v70, v70
	v_rcp_f32_e32 v71, v71
	s_nop 0
	s_nop 1
	v_pk_mul_f32 v[72:73], v[60:61], s[100:101] op_sel_hi:[1,0]
	v_exp_f32_e32 v72, v72
	v_exp_f32_e32 v73, v73
	s_nop 0
	v_pk_add_f32 v[72:73], v[72:73], 1.0 op_sel_hi:[1,0]
	v_rcp_f32_e32 v72, v72
	v_rcp_f32_e32 v73, v73
	s_nop 0
	v_pk_mul_f32 v[62:63], v[62:63], v[66:67]
	v_pk_mul_f32 v[54:55], v[62:63], v[54:55]
	v_pk_mul_f32 v[62:63], v[64:65], v[68:69]
	v_cvt_pk_bf16_f32 v54, v54, v55
	v_pk_mul_f32 v[56:57], v[62:63], v[56:57]
	s_nop 0
	v_cvt_pk_bf16_f32 v55, v56, v57
	v_pk_mul_f32 v[56:57], v[58:59], v[70:71]
	v_add_u32_e32 v58, 0x90, v148
	v_pk_mul_f32 v[50:51], v[56:57], v[50:51]
	v_mad_i64_i32 v[58:59], s[46:47], v58, s9, v[140:141]
	v_cvt_pk_bf16_f32 v56, v50, v51
	v_pk_mul_f32 v[50:51], v[60:61], v[72:73]
	v_lshl_add_u64 v[58:59], v[58:59], 0, v[142:143]
	v_pk_mul_f32 v[50:51], v[50:51], v[52:53]
	s_nop 1
	v_pk_mul_f32 v[52:53], v[48:49], s[100:101] op_sel_hi:[1,0]
	v_exp_f32_e32 v52, v52
	v_exp_f32_e32 v53, v53
	s_nop 0
	v_pk_add_f32 v[52:53], v[52:53], 1.0 op_sel_hi:[1,0]
	v_rcp_f32_e32 v52, v52
	v_rcp_f32_e32 v53, v53
	s_nop 0
	v_cvt_pk_bf16_f32 v57, v50, v51
	s_nop 1
	v_pk_mul_f32 v[50:51], v[46:47], s[100:101] op_sel_hi:[1,0]
	v_exp_f32_e32 v50, v50
	v_exp_f32_e32 v51, v51
	s_nop 0
	v_pk_add_f32 v[50:51], v[50:51], 1.0 op_sel_hi:[1,0]
	v_rcp_f32_e32 v50, v50
	v_rcp_f32_e32 v51, v51
	s_nop 0
	global_store_dwordx4 v[74:75], v[54:57], off
	s_nop 1
	v_pk_mul_f32 v[54:55], v[42:43], s[100:101] op_sel_hi:[1,0]
	v_exp_f32_e32 v54, v54
	v_exp_f32_e32 v55, v55
	s_nop 0
	v_pk_add_f32 v[54:55], v[54:55], 1.0 op_sel_hi:[1,0]
	v_rcp_f32_e32 v54, v54
	v_rcp_f32_e32 v55, v55
	s_nop 0
	s_nop 1
	v_pk_mul_f32 v[56:57], v[44:45], s[100:101] op_sel_hi:[1,0]
	v_exp_f32_e32 v56, v56
	v_exp_f32_e32 v57, v57
	s_nop 0
	v_pk_add_f32 v[56:57], v[56:57], 1.0 op_sel_hi:[1,0]
	v_rcp_f32_e32 v56, v56
	v_rcp_f32_e32 v57, v57
	s_nop 0
	v_pk_mul_f32 v[46:47], v[46:47], v[50:51]
	v_pk_mul_f32 v[38:39], v[46:47], v[38:39]
	v_pk_mul_f32 v[46:47], v[48:49], v[52:53]
	v_cvt_pk_bf16_f32 v38, v38, v39
	v_pk_mul_f32 v[40:41], v[46:47], v[40:41]
	s_nop 0
	v_cvt_pk_bf16_f32 v39, v40, v41
	v_pk_mul_f32 v[40:41], v[42:43], v[54:55]
	v_add_u32_e32 v42, 0xa0, v148
	v_pk_mul_f32 v[34:35], v[40:41], v[34:35]
	v_mad_i64_i32 v[42:43], s[46:47], v42, s9, v[140:141]
	v_cvt_pk_bf16_f32 v40, v34, v35
	v_pk_mul_f32 v[34:35], v[44:45], v[56:57]
	v_lshl_add_u64 v[42:43], v[42:43], 0, v[142:143]
	v_pk_mul_f32 v[34:35], v[34:35], v[36:37]
	s_nop 1
	v_pk_mul_f32 v[36:37], v[32:33], s[100:101] op_sel_hi:[1,0]
	v_exp_f32_e32 v36, v36
	v_exp_f32_e32 v37, v37
	s_nop 0
	v_pk_add_f32 v[36:37], v[36:37], 1.0 op_sel_hi:[1,0]
	v_rcp_f32_e32 v36, v36
	v_rcp_f32_e32 v37, v37
	s_nop 0
	v_cvt_pk_bf16_f32 v41, v34, v35
	s_nop 1
	v_pk_mul_f32 v[34:35], v[30:31], s[100:101] op_sel_hi:[1,0]
	v_exp_f32_e32 v34, v34
	v_exp_f32_e32 v35, v35
	s_nop 0
	v_pk_add_f32 v[34:35], v[34:35], 1.0 op_sel_hi:[1,0]
	v_rcp_f32_e32 v34, v34
	v_rcp_f32_e32 v35, v35
	s_nop 0
	global_store_dwordx4 v[58:59], v[38:41], off
	s_nop 1
	v_pk_mul_f32 v[38:39], v[26:27], s[100:101] op_sel_hi:[1,0]
	v_exp_f32_e32 v38, v38
	v_exp_f32_e32 v39, v39
	s_nop 0
	v_pk_add_f32 v[38:39], v[38:39], 1.0 op_sel_hi:[1,0]
	v_rcp_f32_e32 v38, v38
	v_rcp_f32_e32 v39, v39
	s_nop 0
	s_nop 1
	v_pk_mul_f32 v[40:41], v[28:29], s[100:101] op_sel_hi:[1,0]
	v_exp_f32_e32 v40, v40
	v_exp_f32_e32 v41, v41
	s_nop 0
	v_pk_add_f32 v[40:41], v[40:41], 1.0 op_sel_hi:[1,0]
	v_rcp_f32_e32 v40, v40
	v_rcp_f32_e32 v41, v41
	s_nop 0
	v_pk_mul_f32 v[30:31], v[30:31], v[34:35]
	v_pk_mul_f32 v[22:23], v[30:31], v[22:23]
	v_pk_mul_f32 v[30:31], v[32:33], v[36:37]
	v_cvt_pk_bf16_f32 v22, v22, v23
	v_pk_mul_f32 v[24:25], v[30:31], v[24:25]
	s_nop 0
	v_cvt_pk_bf16_f32 v23, v24, v25
	v_pk_mul_f32 v[24:25], v[26:27], v[38:39]
	v_add_u32_e32 v26, 0xb0, v148
	v_pk_mul_f32 v[18:19], v[24:25], v[18:19]
	v_mad_i64_i32 v[26:27], s[46:47], v26, s9, v[140:141]
	v_cvt_pk_bf16_f32 v24, v18, v19
	v_pk_mul_f32 v[18:19], v[28:29], v[40:41]
	v_lshl_add_u64 v[26:27], v[26:27], 0, v[142:143]
	v_pk_mul_f32 v[18:19], v[18:19], v[20:21]
	s_nop 1
	v_pk_mul_f32 v[20:21], v[16:17], s[100:101] op_sel_hi:[1,0]
	v_exp_f32_e32 v20, v20
	v_exp_f32_e32 v21, v21
	s_nop 0
	v_pk_add_f32 v[20:21], v[20:21], 1.0 op_sel_hi:[1,0]
	v_rcp_f32_e32 v20, v20
	v_rcp_f32_e32 v21, v21
	s_nop 0
	v_cvt_pk_bf16_f32 v25, v18, v19
	s_nop 1
	v_pk_mul_f32 v[18:19], v[14:15], s[100:101] op_sel_hi:[1,0]
	v_exp_f32_e32 v18, v18
	v_exp_f32_e32 v19, v19
	s_nop 0
	v_pk_add_f32 v[18:19], v[18:19], 1.0 op_sel_hi:[1,0]
	v_rcp_f32_e32 v18, v18
	v_rcp_f32_e32 v19, v19
	s_nop 0
	global_store_dwordx4 v[42:43], v[22:25], off
	s_nop 1
	v_pk_mul_f32 v[22:23], v[10:11], s[100:101] op_sel_hi:[1,0]
	v_exp_f32_e32 v22, v22
	v_exp_f32_e32 v23, v23
	s_nop 0
	v_pk_add_f32 v[22:23], v[22:23], 1.0 op_sel_hi:[1,0]
	v_rcp_f32_e32 v22, v22
	v_rcp_f32_e32 v23, v23
	s_nop 0
	s_nop 1
	v_pk_mul_f32 v[24:25], v[12:13], s[100:101] op_sel_hi:[1,0]
	v_exp_f32_e32 v24, v24
	v_exp_f32_e32 v25, v25
	s_nop 0
	v_pk_add_f32 v[24:25], v[24:25], 1.0 op_sel_hi:[1,0]
	v_rcp_f32_e32 v24, v24
	v_rcp_f32_e32 v25, v25
	s_nop 0
	v_pk_mul_f32 v[14:15], v[14:15], v[18:19]
	v_pk_mul_f32 v[6:7], v[14:15], v[6:7]
	v_pk_mul_f32 v[14:15], v[16:17], v[20:21]
	v_cvt_pk_bf16_f32 v6, v6, v7
	v_pk_mul_f32 v[8:9], v[14:15], v[8:9]
	s_mov_b64 s[46:47], s[42:43]
	v_cvt_pk_bf16_f32 v7, v8, v9
	v_pk_mul_f32 v[8:9], v[10:11], v[22:23]
	s_nop 0
	v_pk_mul_f32 v[2:3], v[8:9], v[2:3]
	s_nop 0
	v_cvt_pk_bf16_f32 v8, v2, v3
	v_pk_mul_f32 v[2:3], v[12:13], v[24:25]
	s_nop 0
	v_pk_mul_f32 v[2:3], v[2:3], v[4:5]
	s_nop 0
	v_cvt_pk_bf16_f32 v9, v2, v3
	global_store_dwordx4 v[26:27], v[6:9], off
	s_cbranch_vccz .LBB0_657
	s_waitcnt vmcnt(0)
	s_cmpk_gt_u32 s18, 0xff
	s_cbranch_scc1 .LBB0_664
	s_barrier
